# compiler phase-0 transpose loop restricted to the layer-0 weights (virtual unit index mapped at loop top); layer-1 weight transposes at the end of layer 0's out-projection phase on workgroups >= 64
# baseline (speedup 1.0000x reference)
.LBB0_32:
	s_waitcnt lgkmcnt(7)
	v_cvt_pk_bf16_f32 v4, v4, v5
	s_waitcnt lgkmcnt(6)
	v_cvt_pk_bf16_f32 v5, v6, v7
	s_waitcnt lgkmcnt(5)
	v_cvt_pk_bf16_f32 v6, v8, v9
	s_waitcnt lgkmcnt(3)
	v_cvt_pk_bf16_f32 v8, v12, v13
	v_lshl_add_u32 v12, s24, 6, v23
	v_ashrrev_i32_e32 v13, 31, v12
	v_lshlrev_b64 v[12:13], 11, v[12:13]
	v_lshl_add_u64 v[12:13], s[6:7], 0, v[12:13]
	s_ashr_i32 s9, s8, 31
	v_lshl_add_u64 v[12:13], s[8:9], 1, v[12:13]
	s_add_i32 s23, s23, s18
	v_cvt_pk_bf16_f32 v7, v10, v11
	s_waitcnt lgkmcnt(2)
	v_cvt_pk_bf16_f32 v9, v14, v15
	s_waitcnt lgkmcnt(1)
	v_cvt_pk_bf16_f32 v10, v16, v17
	s_waitcnt lgkmcnt(0)
	v_cvt_pk_bf16_f32 v11, v18, v19
	v_lshl_add_u64 v[12:13], v[12:13], 0, v[2:3]
	s_cmpk_gt_i32 s23, 0x3bf
	global_store_dwordx4 v[12:13], v[4:7], off
	global_store_dwordx4 v[12:13], v[8:11], off offset:16
	s_cbranch_scc1 .LBB0_50
.LBB0_33:
	s_cmpk_lt_u32 s23, 0x2c0
	s_cselect_b32 s27, 0, 0x2c0
	s_add_i32 s27, s27, s23
	s_cmpk_lt_i32 s27, 0x580
	s_cselect_b64 s[10:11], -1, 0
	s_cmpk_gt_i32 s27, 0x57f
	s_mov_b64 s[8:9], -1
	s_cbranch_scc0 .LBB0_35
	s_waitcnt lgkmcnt(0)
	s_load_dwordx16 s[64:79], s[0:1], 0x40
	s_add_i32 s6, s27, 0xfffffa80
	s_lshr_b32 s4, s6, 8
	s_bfe_u32 s25, s6, 0x40004
	s_and_b32 s24, s27, 15
	s_lshl_b64 s[6:7], s[4:5], 22
	s_waitcnt lgkmcnt(0)
	s_add_u32 s12, s78, s6
	s_addc_u32 s13, s79, s7
	s_load_dwordx16 s[76:91], s[0:1], 0x0
	s_lshl_b64 s[6:7], s[4:5], 21
	s_add_u32 s6, s19, s6
	s_addc_u32 s7, s20, s7
	s_mov_b64 s[8:9], 0
.LBB0_35:
	s_andn2_b64 vcc, exec, s[8:9]
	s_mov_b64 s[16:17], 0x400
	s_cbranch_vccnz .LBB0_37
	s_mul_hi_i32 s4, s27, 0x2e8ba2e9
	s_lshr_b32 s6, s4, 31
	s_ashr_i32 s4, s4, 7
	s_add_i32 s4, s4, s6
	s_mul_i32 s6, s4, 0xfffffd40
	s_add_i32 s6, s27, s6
	s_mul_i32 s7, s6, 0xba3
	s_load_dwordx16 s[36:51], s[0:1], 0x0
	s_lshr_b32 s8, s7, 31
	s_ashr_i32 s7, s7, 17
	s_add_i32 s25, s7, s8
	s_mul_i32 s7, s25, 44
	s_sub_i32 s6, s6, s7
	s_mul_i32 s7, s4, 0xb00000
	s_sext_i32_i16 s24, s6
	s_mul_hi_i32 s6, s4, 0xb00000
	s_waitcnt lgkmcnt(0)
	s_add_u32 s12, s50, s7
	s_addc_u32 s13, s51, s6
	s_mul_hi_i32 s7, s4, 0x580000
	s_mul_i32 s4, s4, 0x580000
	s_add_u32 s6, s21, s4
	s_addc_u32 s7, s22, s7
	s_mov_b64 s[16:17], 0xb00
